# 64-bit accumulator clearing also at the Mt / Nt tile starts
# baseline (speedup 1.0000x reference)
.LBB0_322:
	v_mov_b32_e32 v127, 0
	v_mov_b32_e32 v126, 0
	v_mov_b64_e32 v[0:1], 0
	v_mov_b64_e32 v[2:3], 0
	v_mov_b64_e32 v[4:5], 0
	v_mov_b64_e32 v[6:7], 0
	v_mov_b64_e32 v[8:9], 0
	v_mov_b64_e32 v[10:11], 0
	v_mov_b64_e32 v[12:13], 0
	v_mov_b64_e32 v[14:15], 0
	v_mov_b64_e32 v[16:17], 0
	v_mov_b64_e32 v[18:19], 0
	v_mov_b64_e32 v[20:21], 0
	v_mov_b64_e32 v[22:23], 0
	v_mov_b64_e32 v[24:25], 0
	v_mov_b64_e32 v[26:27], 0
	v_mov_b64_e32 v[28:29], 0
	v_mov_b64_e32 v[30:31], 0
	v_mov_b64_e32 v[32:33], 0
	v_mov_b64_e32 v[34:35], 0
	v_mov_b64_e32 v[36:37], 0
	v_mov_b64_e32 v[38:39], 0
	v_mov_b64_e32 v[40:41], 0
	v_mov_b64_e32 v[42:43], 0
	v_mov_b64_e32 v[44:45], 0
	v_mov_b64_e32 v[46:47], 0
	v_mov_b64_e32 v[48:49], 0
	v_mov_b64_e32 v[50:51], 0
	v_mov_b64_e32 v[52:53], 0
	v_mov_b64_e32 v[54:55], 0
	v_mov_b64_e32 v[56:57], 0
	v_mov_b64_e32 v[58:59], 0
	v_mov_b64_e32 v[60:61], 0
	v_mov_b64_e32 v[62:63], 0
	v_mov_b64_e32 v[64:65], 0
	v_mov_b64_e32 v[66:67], 0
	v_mov_b64_e32 v[68:69], 0
	v_mov_b64_e32 v[70:71], 0
	v_mov_b64_e32 v[72:73], 0
	v_mov_b64_e32 v[74:75], 0
	v_mov_b64_e32 v[76:77], 0
	v_mov_b64_e32 v[78:79], 0
	v_mov_b64_e32 v[80:81], 0
	v_mov_b64_e32 v[82:83], 0
	v_mov_b64_e32 v[84:85], 0
	v_mov_b64_e32 v[86:87], 0
	v_mov_b64_e32 v[88:89], 0
	v_mov_b64_e32 v[90:91], 0
	v_mov_b64_e32 v[92:93], 0
	v_mov_b64_e32 v[94:95], 0
	v_mov_b64_e32 v[96:97], 0
	v_mov_b64_e32 v[98:99], 0
	v_mov_b64_e32 v[100:101], 0
	v_mov_b64_e32 v[102:103], 0
	v_mov_b64_e32 v[104:105], 0
	v_mov_b64_e32 v[106:107], 0
	v_mov_b64_e32 v[108:109], 0
	v_mov_b64_e32 v[110:111], 0
	v_mov_b64_e32 v[112:113], 0
	v_mov_b64_e32 v[114:115], 0
	v_mov_b64_e32 v[116:117], 0
	v_mov_b64_e32 v[118:119], 0
	v_mov_b64_e32 v[120:121], 0
	v_mov_b64_e32 v[122:123], 0
	v_mov_b64_e32 v[124:125], 0
	s_and_b64 vcc, exec, s[0:1]
	s_cbranch_vccnz .LBB0_325
	s_add_u32 s28, s28, 0x80080
	s_addc_u32 s29, s29, 0
	s_add_u32 s53, s30, 0x100
	v_mov_b32_e32 v0, 0
	v_mov_b32_e32 v1, 0
	v_mov_b64_e32 v[2:3], 0
	v_mov_b64_e32 v[4:5], 0
	v_mov_b64_e32 v[6:7], 0
	v_mov_b64_e32 v[8:9], 0
	v_mov_b64_e32 v[10:11], 0
	v_mov_b64_e32 v[12:13], 0
	v_mov_b64_e32 v[14:15], 0
	v_mov_b64_e32 v[16:17], 0
	v_mov_b64_e32 v[18:19], 0
	v_mov_b64_e32 v[20:21], 0
	v_mov_b64_e32 v[22:23], 0
	v_mov_b64_e32 v[24:25], 0
	v_mov_b64_e32 v[26:27], 0
	v_mov_b64_e32 v[28:29], 0
	v_mov_b64_e32 v[30:31], 0
	v_mov_b64_e32 v[32:33], 0
	v_mov_b64_e32 v[34:35], 0
	v_mov_b64_e32 v[36:37], 0
	v_mov_b64_e32 v[38:39], 0
	v_mov_b64_e32 v[40:41], 0
	v_mov_b64_e32 v[42:43], 0
	v_mov_b64_e32 v[44:45], 0
	v_mov_b64_e32 v[46:47], 0
	v_mov_b64_e32 v[48:49], 0
	v_mov_b64_e32 v[50:51], 0
	v_mov_b64_e32 v[52:53], 0
	v_mov_b64_e32 v[54:55], 0
	v_mov_b64_e32 v[56:57], 0
	v_mov_b64_e32 v[58:59], 0
	v_mov_b64_e32 v[60:61], 0
	v_mov_b64_e32 v[62:63], 0
	v_mov_b64_e32 v[64:65], 0
	v_mov_b64_e32 v[66:67], 0
	v_mov_b64_e32 v[68:69], 0
	v_mov_b64_e32 v[70:71], 0
	v_mov_b64_e32 v[72:73], 0
	v_mov_b64_e32 v[74:75], 0
	v_mov_b64_e32 v[76:77], 0
	v_mov_b64_e32 v[78:79], 0
	v_mov_b64_e32 v[80:81], 0
	v_mov_b64_e32 v[82:83], 0
	v_mov_b64_e32 v[84:85], 0
	v_mov_b64_e32 v[86:87], 0
	v_mov_b64_e32 v[88:89], 0
	v_mov_b64_e32 v[90:91], 0
	v_mov_b64_e32 v[92:93], 0
	v_mov_b64_e32 v[94:95], 0
	v_mov_b64_e32 v[96:97], 0
	v_mov_b64_e32 v[98:99], 0
	v_mov_b64_e32 v[100:101], 0
	v_mov_b64_e32 v[102:103], 0
	v_mov_b64_e32 v[104:105], 0
	v_mov_b64_e32 v[106:107], 0
	v_mov_b64_e32 v[108:109], 0
	v_mov_b64_e32 v[110:111], 0
	v_mov_b64_e32 v[112:113], 0
	v_mov_b64_e32 v[114:115], 0
	v_mov_b64_e32 v[116:117], 0
	v_mov_b64_e32 v[118:119], 0
	v_mov_b64_e32 v[120:121], 0
	v_mov_b64_e32 v[122:123], 0
	v_mov_b64_e32 v[124:125], 0
	v_mov_b64_e32 v[126:127], 0
	s_addc_u32 s54, s31, 0
	s_mov_b32 s30, 0

.LBB0_339:
	v_mov_b32_e32 v127, 0
	v_mov_b32_e32 v126, 0
	v_mov_b64_e32 v[0:1], 0
	v_mov_b64_e32 v[2:3], 0
	v_mov_b64_e32 v[4:5], 0
	v_mov_b64_e32 v[6:7], 0
	v_mov_b64_e32 v[8:9], 0
	v_mov_b64_e32 v[10:11], 0
	v_mov_b64_e32 v[12:13], 0
	v_mov_b64_e32 v[14:15], 0
	v_mov_b64_e32 v[16:17], 0
	v_mov_b64_e32 v[18:19], 0
	v_mov_b64_e32 v[20:21], 0
	v_mov_b64_e32 v[22:23], 0
	v_mov_b64_e32 v[24:25], 0
	v_mov_b64_e32 v[26:27], 0
	v_mov_b64_e32 v[28:29], 0
	v_mov_b64_e32 v[30:31], 0
	v_mov_b64_e32 v[32:33], 0
	v_mov_b64_e32 v[34:35], 0
	v_mov_b64_e32 v[36:37], 0
	v_mov_b64_e32 v[38:39], 0
	v_mov_b64_e32 v[40:41], 0
	v_mov_b64_e32 v[42:43], 0
	v_mov_b64_e32 v[44:45], 0
	v_mov_b64_e32 v[46:47], 0
	v_mov_b64_e32 v[48:49], 0
	v_mov_b64_e32 v[50:51], 0
	v_mov_b64_e32 v[52:53], 0
	v_mov_b64_e32 v[54:55], 0
	v_mov_b64_e32 v[56:57], 0
	v_mov_b64_e32 v[58:59], 0
	v_mov_b64_e32 v[60:61], 0
	v_mov_b64_e32 v[62:63], 0
	v_mov_b64_e32 v[64:65], 0
	v_mov_b64_e32 v[66:67], 0
	v_mov_b64_e32 v[68:69], 0
	v_mov_b64_e32 v[70:71], 0
	v_mov_b64_e32 v[72:73], 0
	v_mov_b64_e32 v[74:75], 0
	v_mov_b64_e32 v[76:77], 0
	v_mov_b64_e32 v[78:79], 0
	v_mov_b64_e32 v[80:81], 0
	v_mov_b64_e32 v[82:83], 0
	v_mov_b64_e32 v[84:85], 0
	v_mov_b64_e32 v[86:87], 0
	v_mov_b64_e32 v[88:89], 0
	v_mov_b64_e32 v[90:91], 0
	v_mov_b64_e32 v[92:93], 0
	v_mov_b64_e32 v[94:95], 0
	v_mov_b64_e32 v[96:97], 0
	v_mov_b64_e32 v[98:99], 0
	v_mov_b64_e32 v[100:101], 0
	v_mov_b64_e32 v[102:103], 0
	v_mov_b64_e32 v[104:105], 0
	v_mov_b64_e32 v[106:107], 0
	v_mov_b64_e32 v[108:109], 0
	v_mov_b64_e32 v[110:111], 0
	v_mov_b64_e32 v[112:113], 0
	v_mov_b64_e32 v[114:115], 0
	v_mov_b64_e32 v[116:117], 0
	v_mov_b64_e32 v[118:119], 0
	v_mov_b64_e32 v[120:121], 0
	v_mov_b64_e32 v[122:123], 0
	v_mov_b64_e32 v[124:125], 0
	s_and_b64 vcc, exec, s[0:1]
	s_cbranch_vccnz .LBB0_342
	s_add_u32 s28, s28, 0x40080
	s_addc_u32 s29, s29, 0
	s_add_u32 s53, s30, 0x100
	v_mov_b32_e32 v0, 0
	v_mov_b32_e32 v1, 0
	v_mov_b64_e32 v[2:3], 0
	v_mov_b64_e32 v[4:5], 0
	v_mov_b64_e32 v[6:7], 0
	v_mov_b64_e32 v[8:9], 0
	v_mov_b64_e32 v[10:11], 0
	v_mov_b64_e32 v[12:13], 0
	v_mov_b64_e32 v[14:15], 0
	v_mov_b64_e32 v[16:17], 0
	v_mov_b64_e32 v[18:19], 0
	v_mov_b64_e32 v[20:21], 0
	v_mov_b64_e32 v[22:23], 0
	v_mov_b64_e32 v[24:25], 0
	v_mov_b64_e32 v[26:27], 0
	v_mov_b64_e32 v[28:29], 0
	v_mov_b64_e32 v[30:31], 0
	v_mov_b64_e32 v[32:33], 0
	v_mov_b64_e32 v[34:35], 0
	v_mov_b64_e32 v[36:37], 0
	v_mov_b64_e32 v[38:39], 0
	v_mov_b64_e32 v[40:41], 0
	v_mov_b64_e32 v[42:43], 0
	v_mov_b64_e32 v[44:45], 0
	v_mov_b64_e32 v[46:47], 0
	v_mov_b64_e32 v[48:49], 0
	v_mov_b64_e32 v[50:51], 0
	v_mov_b64_e32 v[52:53], 0
	v_mov_b64_e32 v[54:55], 0
	v_mov_b64_e32 v[56:57], 0
	v_mov_b64_e32 v[58:59], 0
	v_mov_b64_e32 v[60:61], 0
	v_mov_b64_e32 v[62:63], 0
	v_mov_b64_e32 v[64:65], 0
	v_mov_b64_e32 v[66:67], 0
	v_mov_b64_e32 v[68:69], 0
	v_mov_b64_e32 v[70:71], 0
	v_mov_b64_e32 v[72:73], 0
	v_mov_b64_e32 v[74:75], 0
	v_mov_b64_e32 v[76:77], 0
	v_mov_b64_e32 v[78:79], 0
	v_mov_b64_e32 v[80:81], 0
	v_mov_b64_e32 v[82:83], 0
	v_mov_b64_e32 v[84:85], 0
	v_mov_b64_e32 v[86:87], 0
	v_mov_b64_e32 v[88:89], 0
	v_mov_b64_e32 v[90:91], 0
	v_mov_b64_e32 v[92:93], 0
	v_mov_b64_e32 v[94:95], 0
	v_mov_b64_e32 v[96:97], 0
	v_mov_b64_e32 v[98:99], 0
	v_mov_b64_e32 v[100:101], 0
	v_mov_b64_e32 v[102:103], 0
	v_mov_b64_e32 v[104:105], 0
	v_mov_b64_e32 v[106:107], 0
	v_mov_b64_e32 v[108:109], 0
	v_mov_b64_e32 v[110:111], 0
	v_mov_b64_e32 v[112:113], 0
	v_mov_b64_e32 v[114:115], 0
	v_mov_b64_e32 v[116:117], 0
	v_mov_b64_e32 v[118:119], 0
	v_mov_b64_e32 v[120:121], 0
	v_mov_b64_e32 v[122:123], 0
	v_mov_b64_e32 v[124:125], 0
	v_mov_b64_e32 v[126:127], 0
	s_addc_u32 s54, s31, 0
	s_mov_b32 s30, 0
